# v23 + attention q-gain hoist / late next-Q wait + nt on attention Q/K/V loads (combination of v28 and v29)
# baseline (speedup 1.0000x reference)
; __device__ __forceinline__ unsigned pk2(float lo, float hi) { f32x2_t v = {lo, hi}; bf16x2_t b = __builtin_convertvector(v, bf16x2_t); return __builtin_bit_cast(unsigned, b); }
; #define LDS_WAIT() asm volatile("s_waitcnt lgkmcnt(0)" ::: "memory")
; __device__ __forceinline__ void attn_unit(const AtArgs& A, unsigned char* lds, int unit, int tid, int wave, int lane) {
;     ...
;             { const bf16* pn = pq0 + (size_t)((st < 3) ? st + 1 : 3) * 16 * QW; qn0 = *(const u32x4*)pn; qn1 = *(const u32x4*)(pn + 8); }
;             norm_rope(qc0, qc1, A.qg, chunk, ROPE + t * 16, 0.125f, x);
;             u32x4 o0, o1; o0.x = pk2(x[0], x[1]); o0.y = pk2(x[2], x[3]); o0.z = pk2(x[4], x[5]); o0.w = pk2(x[6], x[7]); o1.x = pk2(x[8], x[9]); o1.y = pk2(x[10], x[11]); o1.z = pk2(x[12], x[13]); o1.w = pk2(x[14], x[15]);
;             *(u32x4*)(QS + row * QST + chunk * 16) = o0; *(u32x4*)(QS + row * QST + chunk * 16 + 8) = o1;
;         }
;         LDS_WAIT();
;         const bf16x8 qa0 = *(const bf16x8*)(QS + fr * QST + fq * 8), qa1 = *(const bf16x8*)(QS + fr * QST + 32 + fq * 8);
;         f32x4 sc[9];
; #pragma unroll
;         for (int kt = 0; kt < 9; ++kt) {
;             const int key = (q0 / 16 + kt) * 16 + fr;
;             const bf16x8 kb0 = *(const bf16x8*)(KS + key * KST + fq * 8), kb1 = *(const bf16x8*)(KS + key * KST + 32 + fq * 8);
;             f32x4 a = (f32x4){0.f, 0.f, 0.f, 0.f};
;             a = __builtin_amdgcn_mfma_f32_16x16x32_bf16(qa0, kb0, a, 0, 0, 0); a = __builtin_amdgcn_mfma_f32_16x16x32_bf16(qa1, kb1, a, 0, 0, 0);
; #pragma unroll
;             for (int r = 0; r < 4; ++r) {
;                 const int qi = q0 + fq * 4 + r;
;                 const bool ok = (key > qi) && (key <= qi + 128) && (nb > 0 || key >= 128);
;                 a[r] = ok ? a[r] : -1e30f;
;             }
;             sc[kt] = a;
;         }
.LBB0_510:
	s_or_b64 exec, exec, s[0:1]
	s_cmp_lg_u32 s2, 48
	s_cselect_b32 s6, s3, 0x21000
	v_lshl_add_u64 v[4:5], s[6:7], 1, v[50:51]
	global_load_dwordx4 v[0:3], v[4:5], off offset:16 nt
	s_nop 0
	global_load_dwordx4 v[4:7], v[4:5], off nt
	s_nop 0
	v_pk_mul_f32 v[18:19], v[60:61], s[14:15] op_sel_hi:[1,0]
	v_pk_mul_f32 v[20:21], v[28:29], s[14:15] op_sel_hi:[1,0]
	v_pk_mul_f32 v[22:23], v[24:25], s[14:15] op_sel_hi:[1,0]
	v_pk_mul_f32 v[12:13], v[12:13], s[14:15] op_sel_hi:[1,0]
	v_pk_mul_f32 v[24:25], v[8:9], s[14:15] op_sel_hi:[1,0]
	v_pk_mul_f32 v[26:27], v[10:11], s[14:15] op_sel_hi:[1,0]
	v_pk_mul_f32 v[14:15], v[14:15], s[14:15] op_sel_hi:[1,0]
	v_pk_mul_f32 v[16:17], v[16:17], s[14:15] op_sel_hi:[1,0]
	v_cvt_pk_bf16_f32 v8, v18, v19
	v_cvt_pk_bf16_f32 v9, v20, v21
	v_cvt_pk_bf16_f32 v10, v22, v23
	v_cvt_pk_bf16_f32 v11, v12, v13
	v_cvt_pk_bf16_f32 v12, v24, v25
	v_cvt_pk_bf16_f32 v13, v26, v27
	v_cvt_pk_bf16_f32 v14, v14, v15
	v_cvt_pk_bf16_f32 v15, v16, v17
	ds_write_b128 v75, v[8:11]
	ds_write_b128 v75, v[12:15] offset:16
	s_waitcnt lgkmcnt(0)
	ds_read_b128 v[12:15], v76
	ds_read_b128 v[8:11], v76 offset:64
	ds_read_b128 v[16:19], v95
	ds_read_b128 v[20:23], v95 offset:64
	s_waitcnt lgkmcnt(1)
	v_mfma_f32_16x16x32_bf16 v[16:19], v[12:15], v[16:19], 0
	v_add_u32_e32 v30, s2, v85
	v_add_u32_e32 v31, s2, v88
	v_add_u32_e32 v58, 1, v31
	s_waitcnt lgkmcnt(0)
	v_mfma_f32_16x16x32_bf16 v[16:19], v[8:11], v[20:23], v[16:19]
	v_add_u32_e32 v20, 0xffffff80, v30
	v_cmp_ge_i32_e32 vcc, v31, v20
	s_and_b64 s[0:1], s[42:43], vcc
	s_and_b64 vcc, s[16:17], s[0:1]
	v_cmp_ge_i32_e64 s[0:1], v58, v20
	s_nop 2
	v_cndmask_b32_e32 v29, v93, v16, vcc
	v_cmp_gt_i32_e32 vcc, v30, v58
	s_and_b64 s[0:1], vcc, s[0:1]
	s_and_b64 vcc, s[16:17], s[0:1]
	v_add_u32_e32 v59, 2, v31
	ds_read_b128 v[96:99], v95 offset:2304
	ds_read_b128 v[100:103], v95 offset:2368
	v_cndmask_b32_e32 v22, v93, v17, vcc
	v_cmp_gt_i32_e32 vcc, v30, v59
	v_cmp_ge_i32_e64 s[0:1], v59, v20
	s_and_b64 s[0:1], vcc, s[0:1]
	s_and_b64 vcc, s[16:17], s[0:1]
	v_add_u32_e32 v60, 3, v31
	v_cndmask_b32_e32 v18, v93, v18, vcc
	v_cmp_gt_i32_e32 vcc, v30, v60
	v_cmp_ge_i32_e64 s[0:1], v60, v20
	s_waitcnt lgkmcnt(1)
	v_mfma_f32_16x16x32_bf16 v[96:99], v[12:15], v[96:99], 0
	s_and_b64 s[0:1], vcc, s[0:1]
	s_add_i32 s6, s4, s2
	s_and_b64 vcc, s[16:17], s[0:1]
	s_add_i32 s0, s6, 16
	s_cmpk_gt_u32 s0, 0x7f
	v_cndmask_b32_e32 v16, v93, v19, vcc
	v_add_u32_e32 v17, 16, v30
	s_waitcnt lgkmcnt(0)
	v_mfma_f32_16x16x32_bf16 v[96:99], v[8:11], v[100:103], v[96:99]
	v_add_u32_e32 v19, 0xffffff90, v30
	s_cselect_b64 s[0:1], -1, 0
	s_or_b64 s[10:11], s[16:17], s[0:1]
	v_cmp_gt_i32_e32 vcc, v17, v31
	v_cmp_ge_i32_e64 s[0:1], v31, v19
	s_and_b64 s[0:1], vcc, s[0:1]
	s_and_b64 vcc, s[0:1], s[10:11]
	s_nop 0
	v_cndmask_b32_e32 v96, v93, v96, vcc
	v_cmp_gt_i32_e32 vcc, v17, v58
	v_cmp_ge_i32_e64 s[0:1], v58, v19
	s_and_b64 s[0:1], vcc, s[0:1]
	s_and_b64 vcc, s[0:1], s[10:11]
	v_cndmask_b32_e32 v26, v93, v97, vcc
	v_cmp_gt_i32_e32 vcc, v17, v59
	v_cmp_ge_i32_e64 s[0:1], v59, v19
	s_and_b64 s[0:1], vcc, s[0:1]
	s_and_b64 vcc, s[0:1], s[10:11]
	v_cndmask_b32_e32 v20, v93, v98, vcc
	v_cmp_gt_i32_e32 vcc, v17, v60
	v_cmp_ge_i32_e64 s[0:1], v60, v19
	s_and_b64 s[0:1], vcc, s[0:1]
	s_and_b64 vcc, s[0:1], s[10:11]
	v_cndmask_b32_e32 v17, v93, v99, vcc
	ds_read_b128 v[98:101], v95 offset:4608
	ds_read_b128 v[108:111], v95 offset:4672
	s_waitcnt lgkmcnt(1)
	v_mfma_f32_16x16x32_bf16 v[98:101], v[12:15], v[98:101], 0
	s_add_i32 s0, s6, 32
	s_cmpk_gt_u32 s0, 0x7f
	v_add_u32_e32 v19, 32, v30
	s_waitcnt lgkmcnt(0)
	v_mfma_f32_16x16x32_bf16 v[100:103], v[8:11], v[108:111], v[98:101]
	v_add_u32_e32 v21, 0xffffffa0, v30
	s_cselect_b64 s[0:1], -1, 0
	s_or_b64 s[10:11], s[16:17], s[0:1]
	v_cmp_gt_i32_e32 vcc, v19, v31
	v_cmp_ge_i32_e64 s[0:1], v31, v21
	s_and_b64 s[0:1], vcc, s[0:1]
	s_and_b64 vcc, s[0:1], s[10:11]
	s_nop 0
	v_cndmask_b32_e32 v100, v93, v100, vcc
	v_cmp_gt_i32_e32 vcc, v19, v58
	v_cmp_ge_i32_e64 s[0:1], v58, v21
	s_and_b64 s[0:1], vcc, s[0:1]
	s_and_b64 vcc, s[0:1], s[10:11]
	ds_read_b128 v[108:111], v95 offset:6912
	ds_read_b128 v[112:115], v95 offset:6976
	v_cndmask_b32_e32 v56, v93, v101, vcc
	v_cmp_gt_i32_e32 vcc, v19, v59
	v_cmp_ge_i32_e64 s[0:1], v59, v21
	s_and_b64 s[0:1], vcc, s[0:1]
	s_and_b64 vcc, s[0:1], s[10:11]
	v_cndmask_b32_e32 v23, v93, v102, vcc
	v_cmp_gt_i32_e32 vcc, v19, v60
	v_cmp_ge_i32_e64 s[0:1], v60, v21
	s_waitcnt lgkmcnt(1)
	v_mfma_f32_16x16x32_bf16 v[108:111], v[12:15], v[108:111], 0
	s_and_b64 s[0:1], vcc, s[0:1]
	s_and_b64 vcc, s[0:1], s[10:11]
	s_add_i32 s0, s6, 48
	s_cmpk_gt_u32 s0, 0x7f
	v_add_u32_e32 v21, 48, v30
	s_waitcnt lgkmcnt(0)
	v_mfma_f32_16x16x32_bf16 v[108:111], v[8:11], v[112:115], v[108:111]
	v_add_u32_e32 v25, 0xffffffb0, v30
	s_cselect_b64 s[0:1], -1, 0
	v_cndmask_b32_e32 v19, v93, v103, vcc
	s_or_b64 s[10:11], s[16:17], s[0:1]
	v_cmp_gt_i32_e32 vcc, v21, v31
	v_cmp_ge_i32_e64 s[0:1], v31, v25
	s_and_b64 s[0:1], vcc, s[0:1]
	s_and_b64 vcc, s[0:1], s[10:11]
	v_cndmask_b32_e32 v103, v93, v108, vcc
	v_cmp_gt_i32_e32 vcc, v21, v58
	v_cmp_ge_i32_e64 s[0:1], v58, v25
	s_and_b64 s[0:1], vcc, s[0:1]
	s_and_b64 vcc, s[0:1], s[10:11]
	v_cndmask_b32_e32 v97, v93, v109, vcc
	v_cmp_gt_i32_e32 vcc, v21, v59
	v_cmp_ge_i32_e64 s[0:1], v59, v25
	s_and_b64 s[0:1], vcc, s[0:1]
	s_and_b64 vcc, s[0:1], s[10:11]
	v_cndmask_b32_e32 v27, v93, v110, vcc
	v_cmp_gt_i32_e32 vcc, v21, v60
	v_cmp_ge_i32_e64 s[0:1], v60, v25
	s_and_b64 s[0:1], vcc, s[0:1]
	s_and_b64 vcc, s[0:1], s[10:11]
	v_cndmask_b32_e32 v21, v93, v111, vcc
	ds_read_b128 v[108:111], v95 offset:9216
	ds_read_b128 v[112:115], v95 offset:9280
	s_waitcnt lgkmcnt(1)
; __device__ __forceinline__ void attn_unit(const AtArgs& A, unsigned char* lds, int unit, int tid, int wave, int lane) {
;     ...
; #pragma unroll
;         for (int kt = 0; kt < 9; ++kt) {
;             const int key = (q0 / 16 + kt) * 16 + fr;
;             const bf16x8 kb0 = *(const bf16x8*)(KS + key * KST + fq * 8), kb1 = *(const bf16x8*)(KS + key * KST + 32 + fq * 8);
;             f32x4 a = (f32x4){0.f, 0.f, 0.f, 0.f};
;             a = __builtin_amdgcn_mfma_f32_16x16x32_bf16(qa0, kb0, a, 0, 0, 0); a = __builtin_amdgcn_mfma_f32_16x16x32_bf16(qa1, kb1, a, 0, 0, 0);
; #pragma unroll
;             for (int r = 0; r < 4; ++r) {
;                 const int qi = q0 + fq * 4 + r;
;                 const bool ok = (key > qi) && (key <= qi + 128) && (nb > 0 || key >= 128);
;                 a[r] = ok ? a[r] : -1e30f;
;             }
;             sc[kt] = a;
;         }
	v_mfma_f32_16x16x32_bf16 v[108:111], v[12:15], v[108:111], 0
	s_add_i32 s0, s6, 64
	s_cmpk_gt_u32 s0, 0x7f
	v_add_u32_e32 v25, 64, v30
	s_waitcnt lgkmcnt(0)
	v_mfma_f32_16x16x32_bf16 v[108:111], v[8:11], v[112:115], v[108:111]
	v_subrev_u32_e32 v28, 64, v30
	s_cselect_b64 s[0:1], -1, 0
	s_or_b64 s[10:11], s[16:17], s[0:1]
	v_cmp_gt_i32_e32 vcc, v25, v31
	v_cmp_ge_i32_e64 s[0:1], v31, v28
	s_and_b64 s[0:1], vcc, s[0:1]
	s_and_b64 vcc, s[0:1], s[10:11]
	s_nop 0
	v_cndmask_b32_e32 v116, v93, v108, vcc
	v_cmp_gt_i32_e32 vcc, v25, v58
	v_cmp_ge_i32_e64 s[0:1], v58, v28
	s_and_b64 s[0:1], vcc, s[0:1]
	s_and_b64 vcc, s[0:1], s[10:11]
	v_cndmask_b32_e32 v101, v93, v109, vcc
	v_cmp_gt_i32_e32 vcc, v25, v59
	v_cmp_ge_i32_e64 s[0:1], v59, v28
	s_and_b64 s[0:1], vcc, s[0:1]
	s_and_b64 vcc, s[0:1], s[10:11]
	v_cndmask_b32_e32 v57, v93, v110, vcc
	v_cmp_gt_i32_e32 vcc, v25, v60
	v_cmp_ge_i32_e64 s[0:1], v60, v28
	s_and_b64 s[0:1], vcc, s[0:1]
	s_and_b64 vcc, s[0:1], s[10:11]
	v_cndmask_b32_e32 v25, v93, v111, vcc
	ds_read_b128 v[108:111], v95 offset:11520
	ds_read_b128 v[112:115], v95 offset:11584
	s_waitcnt lgkmcnt(1)
	v_mfma_f32_16x16x32_bf16 v[108:111], v[12:15], v[108:111], 0
	s_add_i32 s0, s6, 0x50
	s_cmpk_gt_u32 s0, 0x7f
	v_add_u32_e32 v28, 0x50, v30
	s_waitcnt lgkmcnt(0)
	v_mfma_f32_16x16x32_bf16 v[108:111], v[8:11], v[112:115], v[108:111]
	v_subrev_u32_e32 v61, 48, v30
	s_cselect_b64 s[0:1], -1, 0
	s_or_b64 s[10:11], s[16:17], s[0:1]
	v_cmp_gt_i32_e32 vcc, v28, v31
	v_cmp_ge_i32_e64 s[0:1], v31, v61
	s_and_b64 s[0:1], vcc, s[0:1]
	s_and_b64 vcc, s[0:1], s[10:11]
	s_nop 0
	v_cndmask_b32_e32 v117, v93, v108, vcc
	v_cmp_gt_i32_e32 vcc, v28, v58
	v_cmp_ge_i32_e64 s[0:1], v58, v61
	s_and_b64 s[0:1], vcc, s[0:1]
	s_and_b64 vcc, s[0:1], s[10:11]
	v_cndmask_b32_e32 v118, v93, v109, vcc
	v_cmp_gt_i32_e32 vcc, v28, v59
	v_cmp_ge_i32_e64 s[0:1], v59, v61
	s_and_b64 s[0:1], vcc, s[0:1]
	s_and_b64 vcc, s[0:1], s[10:11]
	v_cndmask_b32_e32 v98, v93, v110, vcc
	v_cmp_gt_i32_e32 vcc, v28, v60
	v_cmp_ge_i32_e64 s[0:1], v60, v61
	s_and_b64 s[0:1], vcc, s[0:1]
	s_and_b64 vcc, s[0:1], s[10:11]
	v_cndmask_b32_e32 v28, v93, v111, vcc
	ds_read_b128 v[108:111], v95 offset:13824
	ds_read_b128 v[112:115], v95 offset:13888
	s_waitcnt lgkmcnt(1)
	v_mfma_f32_16x16x32_bf16 v[108:111], v[12:15], v[108:111], 0
	s_add_i32 s0, s6, 0x60
	s_cmpk_gt_u32 s0, 0x7f
	v_add_u32_e32 v61, 0x60, v30
	s_waitcnt lgkmcnt(0)
	v_mfma_f32_16x16x32_bf16 v[108:111], v[8:11], v[112:115], v[108:111]
	v_subrev_u32_e32 v99, 32, v30
	s_cselect_b64 s[0:1], -1, 0
	s_or_b64 s[10:11], s[16:17], s[0:1]
	v_cmp_gt_i32_e32 vcc, v61, v31
	v_cmp_ge_i32_e64 s[0:1], v31, v99
	s_and_b64 s[0:1], vcc, s[0:1]
	s_and_b64 vcc, s[0:1], s[10:11]
	s_nop 0
	v_cndmask_b32_e32 v119, v93, v108, vcc
	v_cmp_gt_i32_e32 vcc, v61, v58
	v_cmp_ge_i32_e64 s[0:1], v58, v99
	s_and_b64 s[0:1], vcc, s[0:1]
	s_and_b64 vcc, s[0:1], s[10:11]
	v_cndmask_b32_e32 v120, v93, v109, vcc
	v_cmp_gt_i32_e32 vcc, v61, v59
	v_cmp_ge_i32_e64 s[0:1], v59, v99
	s_and_b64 s[0:1], vcc, s[0:1]
	s_and_b64 vcc, s[0:1], s[10:11]
	v_cndmask_b32_e32 v102, v93, v110, vcc
	v_cmp_gt_i32_e32 vcc, v61, v60
	v_cmp_ge_i32_e64 s[0:1], v60, v99
	s_and_b64 s[0:1], vcc, s[0:1]
	s_and_b64 vcc, s[0:1], s[10:11]
	v_cndmask_b32_e32 v61, v93, v111, vcc
	ds_read_b128 v[108:111], v95 offset:16128
	ds_read_b128 v[112:115], v95 offset:16192
	s_waitcnt lgkmcnt(1)
	v_mfma_f32_16x16x32_bf16 v[108:111], v[12:15], v[108:111], 0
	s_addk_i32 s6, 0x70
	s_cmpk_gt_u32 s6, 0x7f
	v_add_u32_e32 v99, 0x70, v30
	s_waitcnt lgkmcnt(0)
	v_mfma_f32_16x16x32_bf16 v[108:111], v[8:11], v[112:115], v[108:111]
	v_add_u32_e32 v112, -16, v30
	s_cselect_b64 s[0:1], -1, 0
	s_or_b64 s[10:11], s[16:17], s[0:1]
	v_cmp_gt_i32_e32 vcc, v99, v31
	v_cmp_ge_i32_e64 s[0:1], v31, v112
	s_and_b64 s[0:1], vcc, s[0:1]
	s_and_b64 vcc, s[0:1], s[10:11]
	s_nop 0
	v_cndmask_b32_e32 v121, v93, v108, vcc
	v_cmp_gt_i32_e32 vcc, v99, v58
	v_cmp_ge_i32_e64 s[0:1], v58, v112
	s_and_b64 s[0:1], vcc, s[0:1]
	s_and_b64 vcc, s[0:1], s[10:11]
	v_cndmask_b32_e32 v122, v93, v109, vcc
	v_cmp_gt_i32_e32 vcc, v99, v59
	v_cmp_ge_i32_e64 s[0:1], v59, v112
	s_and_b64 s[0:1], vcc, s[0:1]
	s_and_b64 vcc, s[0:1], s[10:11]
	v_cndmask_b32_e32 v123, v93, v110, vcc
	v_cmp_gt_i32_e32 vcc, v99, v60
	v_cmp_ge_i32_e64 s[0:1], v60, v112
	s_and_b64 s[0:1], vcc, s[0:1]
	s_and_b64 vcc, s[0:1], s[10:11]
	v_cndmask_b32_e32 v99, v93, v111, vcc
	ds_read_b128 v[108:111], v95 offset:18432
	ds_read_b128 v[112:115], v95 offset:18496
	s_waitcnt lgkmcnt(1)
	v_mfma_f32_16x16x32_bf16 v[12:15], v[12:15], v[108:111], 0
	v_add_u32_e32 v124, 0x80, v30
	v_cmp_gt_i32_e32 vcc, v124, v31
	v_cmp_ge_i32_e64 s[0:1], v31, v30
	s_waitcnt lgkmcnt(0)
; __device__ __forceinline__ unsigned f2bf(float f) { return pk2(f, f) & 0xffffu; }
; __device__ __forceinline__ float row16_sum(float v) { v += dpp_perm<0xB1, 0xF>(v); v += dpp_perm<0x4E, 0xF>(v); v += dpp_perm<0x141, 0xF>(v); v += dpp_perm<0x140, 0xF>(v); return v; }
; __device__ __forceinline__ float row16_max(float v) { v = fmaxf(v, dpp_perm<0xB1, 0xF>(v)); v = fmaxf(v, dpp_perm<0x4E, 0xF>(v)); v = fmaxf(v, dpp_perm<0x141, 0xF>(v)); v = fmaxf(v, dpp_perm<0x140, 0xF>(v)); return v; }
; __device__ __forceinline__ void attn_unit(const AtArgs& A, unsigned char* lds, int unit, int tid, int wave, int lane) {
;     ...
;             a = __builtin_amdgcn_mfma_f32_16x16x32_bf16(qa0, kb0, a, 0, 0, 0); a = __builtin_amdgcn_mfma_f32_16x16x32_bf16(qa1, kb1, a, 0, 0, 0);
; #pragma unroll
;             for (int r = 0; r < 4; ++r) {
;                 const int qi = q0 + fq * 4 + r;
;                 const bool ok = (key > qi) && (key <= qi + 128) && (nb > 0 || key >= 128);
;                 a[r] = ok ? a[r] : -1e30f;
;             }
;             sc[kt] = a;
;         }
;         float m4[4], s4[4];
; #pragma unroll
;         for (int r = 0; r < 4; ++r) {
;             float m = sc[0][r];
; #pragma unroll
;             for (int kt = 1; kt < 9; ++kt) m = fmaxf(m, sc[kt][r]);
;             m = row16_max(m);
;             m4[r] = fmaxf(m, sink);
;             float s = 0.f;
; #pragma unroll
;             for (int kt = 0; kt < 9; ++kt) { const float e = __expf(sc[kt][r] - m4[r]); sc[kt][r] = e; s += e; }
;             s = row16_sum(s);
;             s4[r] = __builtin_amdgcn_rcpf(s + __expf(sink - m4[r]));
;         }
; #pragma unroll
;         for (int kt = 0; kt < 9; ++kt)
; #pragma unroll
;             for (int r = 0; r < 4; ++r) PS[(fq * 4 + r) * PST + kt * 16 + fr] = (bf16)f2bf(sc[kt][r] * s4[r]);
	v_mfma_f32_16x16x32_bf16 v[8:11], v[8:11], v[112:115], v[12:15]
	s_and_b64 vcc, vcc, s[0:1]
	v_cmp_ge_i32_e64 s[0:1], v58, v30
	v_add_u32_e32 v24, 0x900, v95
	v_mov_b32_e32 v95, 0
	v_mov_b32_e32 v108, 0
	s_nop 2
	v_cndmask_b32_e32 v8, v93, v8, vcc
	v_cmp_gt_i32_e32 vcc, v124, v58
	s_and_b64 vcc, vcc, s[0:1]
	v_cmp_ge_i32_e64 s[0:1], v59, v30
	v_cndmask_b32_e32 v58, v93, v9, vcc
	v_max3_f32 v9, v29, v96, v100
	v_cmp_gt_i32_e32 vcc, v124, v59
	v_max3_f32 v9, v9, v103, v116
	s_and_b64 vcc, vcc, s[0:1]
	v_max3_f32 v9, v9, v117, v119
	v_cndmask_b32_e32 v59, v93, v10, vcc
	v_max3_f32 v9, v9, v121, v8
	v_mov_b32_e32 v10, 0
	v_cmp_ge_i32_e64 s[0:1], v60, v30
	v_cmp_gt_i32_e32 vcc, v124, v60
	v_mov_b32_dpp v10, v9 quad_perm:[1,0,3,2] row_mask:0xf bank_mask:0xf
	v_max_f32_e32 v10, v10, v10
	v_max_f32_e32 v9, v9, v10
	v_mov_b32_e32 v10, 0
	s_and_b64 vcc, vcc, s[0:1]
	v_cndmask_b32_e32 v31, v93, v11, vcc
	v_mov_b32_dpp v10, v9 quad_perm:[2,3,0,1] row_mask:0xf bank_mask:0xf
	v_max_f32_e32 v10, v10, v10
	v_max_f32_e32 v9, v9, v10
	v_mov_b32_e32 v10, 0
	v_mov_b32_e32 v110, 0
	s_add_i32 s2, s2, 16
	v_mov_b32_dpp v10, v9 row_half_mirror row_mask:0xf bank_mask:0xf
	v_max_f32_e32 v10, v10, v10
	v_max_f32_e32 v9, v9, v10
	v_mov_b32_e32 v10, 0
	s_add_i32 s3, s3, 0xb000
	s_nop 0
	v_mov_b32_dpp v10, v9 row_mirror row_mask:0xf bank_mask:0xf
	v_max3_f32 v30, v9, v10, v38
	v_sub_f32_e32 v10, v96, v30
	v_mul_f32_e32 v10, 0x3fb8aa3b, v10
	v_sub_f32_e32 v9, v29, v30
	v_exp_f32_e32 v29, v10
	v_sub_f32_e32 v10, v100, v30
	v_mul_f32_e32 v9, 0x3fb8aa3b, v9
	v_mul_f32_e32 v10, 0x3fb8aa3b, v10
	v_exp_f32_e32 v14, v9
	v_exp_f32_e32 v15, v10
	v_sub_f32_e32 v10, v103, v30
	v_mul_f32_e32 v10, 0x3fb8aa3b, v10
	v_exp_f32_e32 v12, v10
	v_sub_f32_e32 v10, v116, v30
	v_sub_f32_e32 v11, v117, v30
	v_mul_f32_e32 v10, 0x3fb8aa3b, v10
	v_mul_f32_e32 v11, 0x3fb8aa3b, v11
	v_add_f32_e32 v9, 0, v14
	v_exp_f32_e32 v10, v10
	v_exp_f32_e32 v13, v11
	v_sub_f32_e32 v11, v119, v30
	v_add_f32_e32 v9, v29, v9
	v_mul_f32_e32 v11, 0x3fb8aa3b, v11
	v_add_f32_e32 v9, v15, v9
	v_exp_f32_e32 v11, v11
	v_add_f32_e32 v9, v12, v9
	v_add_f32_e32 v9, v10, v9
	v_add_f32_e32 v9, v13, v9
	v_add_f32_e32 v60, v11, v9
	v_sub_f32_e32 v9, v121, v30
	v_mul_f32_e32 v9, 0x3fb8aa3b, v9
	v_sub_f32_e32 v8, v8, v30
	v_exp_f32_e32 v9, v9
	v_mul_f32_e32 v8, 0x3fb8aa3b, v8
	v_exp_f32_e32 v8, v8
	v_sub_f32_e32 v30, v38, v30
	v_add_f32_e32 v60, v9, v60
	v_mul_f32_e32 v30, 0x3fb8aa3b, v30
	v_add_f32_e32 v60, v8, v60
	v_exp_f32_e32 v30, v30
	s_nop 0
	v_add_f32_dpp v60, v60, v60 quad_perm:[1,0,3,2] row_mask:0xf bank_mask:0xf bound_ctrl:1
	s_nop 1
	v_add_f32_dpp v60, v60, v60 quad_perm:[2,3,0,1] row_mask:0xf bank_mask:0xf bound_ctrl:1
	s_nop 1
	v_add_f32_dpp v60, v60, v60 row_half_mirror row_mask:0xf bank_mask:0xf bound_ctrl:1
	s_nop 1
	v_add_f32_dpp v60, v60, v60 row_mirror row_mask:0xf bank_mask:0xf bound_ctrl:1
	v_add_f32_e32 v30, v30, v60
	v_max3_f32 v60, v22, v26, v56
	v_max3_f32 v60, v60, v97, v101
	v_max3_f32 v60, v60, v118, v120
	v_max3_f32 v60, v60, v122, v58
	v_rcp_f32_e32 v30, v30
	s_nop 0
	v_mov_b32_dpp v95, v60 quad_perm:[1,0,3,2] row_mask:0xf bank_mask:0xf
	v_max_f32_e32 v95, v95, v95
	v_max_f32_e32 v60, v60, v95
	v_mov_b32_e32 v95, 0
	v_mul_f32_e32 v14, v14, v30
	v_mul_f32_e32 v10, v10, v30
	v_mov_b32_dpp v95, v60 quad_perm:[2,3,0,1] row_mask:0xf bank_mask:0xf
	v_max_f32_e32 v95, v95, v95
	v_max_f32_e32 v60, v60, v95
	v_mov_b32_e32 v95, 0
	v_cvt_pk_bf16_f32 v14, v14, s0
	v_cvt_pk_bf16_f32 v10, v10, s0
	v_mov_b32_dpp v95, v60 row_half_mirror row_mask:0xf bank_mask:0xf
	v_max_f32_e32 v95, v95, v95
	v_max_f32_e32 v60, v60, v95
	v_mov_b32_e32 v95, 0
	ds_write_b16 v79, v14
	ds_write_b16 v79, v10 offset:128
	v_mov_b32_dpp v95, v60 row_mirror row_mask:0xf bank_mask:0xf
	v_max3_f32 v60, v60, v95, v38
	v_sub_f32_e32 v22, v22, v60
	v_mul_f32_e32 v22, 0x3fb8aa3b, v22
	v_sub_f32_e32 v26, v26, v60
	v_exp_f32_e32 v22, v22
	v_mul_f32_e32 v26, 0x3fb8aa3b, v26
	v_sub_f32_e32 v56, v56, v60
	v_exp_f32_e32 v26, v26
	v_mul_f32_e32 v56, 0x3fb8aa3b, v56
	v_sub_f32_e32 v96, v97, v60
	v_exp_f32_e32 v56, v56
	v_mul_f32_e32 v96, 0x3fb8aa3b, v96
	v_sub_f32_e32 v97, v101, v60
	v_exp_f32_e32 v96, v96
	v_mul_f32_e32 v97, 0x3fb8aa3b, v97
	v_sub_f32_e32 v100, v118, v60
	v_add_f32_e32 v95, 0, v22
	v_exp_f32_e32 v97, v97
	v_mul_f32_e32 v100, 0x3fb8aa3b, v100
	v_sub_f32_e32 v101, v120, v60
	v_add_f32_e32 v95, v26, v95
	v_exp_f32_e32 v100, v100
	v_mul_f32_e32 v101, 0x3fb8aa3b, v101
	v_sub_f32_e32 v103, v122, v60
	v_add_f32_e32 v95, v56, v95
	v_exp_f32_e32 v101, v101
	v_mul_f32_e32 v103, 0x3fb8aa3b, v103
	v_sub_f32_e32 v58, v58, v60
	v_add_f32_e32 v95, v96, v95
	v_exp_f32_e32 v103, v103
	v_mul_f32_e32 v58, 0x3fb8aa3b, v58
	v_add_f32_e32 v95, v97, v95
	v_exp_f32_e32 v58, v58
	v_add_f32_e32 v95, v100, v95
	v_add_f32_e32 v95, v101, v95
	v_add_f32_e32 v95, v103, v95
	v_sub_f32_e32 v60, v38, v60
	v_add_f32_e32 v95, v58, v95
	v_mul_f32_e32 v60, 0x3fb8aa3b, v60
	v_exp_f32_e32 v60, v60
	v_add_f32_dpp v95, v95, v95 quad_perm:[1,0,3,2] row_mask:0xf bank_mask:0xf bound_ctrl:1
	v_mul_f32_e32 v12, v12, v30
	v_mul_f32_e32 v9, v9, v30
	v_add_f32_dpp v95, v95, v95 quad_perm:[2,3,0,1] row_mask:0xf bank_mask:0xf bound_ctrl:1
	v_mul_f32_e32 v8, v8, v30
	v_cvt_pk_bf16_f32 v12, v12, s0
	v_add_f32_dpp v95, v95, v95 row_half_mirror row_mask:0xf bank_mask:0xf bound_ctrl:1
	v_cvt_pk_bf16_f32 v9, v9, s0
	v_cvt_pk_bf16_f32 v8, v8, s0
	v_add_f32_dpp v95, v95, v95 row_mirror row_mask:0xf bank_mask:0xf bound_ctrl:1
	v_add_f32_e32 v60, v60, v95
	v_max3_f32 v95, v18, v20, v23
	v_max3_f32 v95, v95, v27, v57
	v_max3_f32 v95, v95, v98, v102
	v_max3_f32 v95, v95, v123, v59
; __device__ __forceinline__ unsigned f2bf(float f) { return pk2(f, f) & 0xffffu; }
; __device__ __forceinline__ float row16_sum(float v) { v += dpp_perm<0xB1, 0xF>(v); v += dpp_perm<0x4E, 0xF>(v); v += dpp_perm<0x141, 0xF>(v); v += dpp_perm<0x140, 0xF>(v); return v; }
; __device__ __forceinline__ float row16_max(float v) { v = fmaxf(v, dpp_perm<0xB1, 0xF>(v)); v = fmaxf(v, dpp_perm<0x4E, 0xF>(v)); v = fmaxf(v, dpp_perm<0x141, 0xF>(v)); v = fmaxf(v, dpp_perm<0x140, 0xF>(v)); return v; }
; __device__ __forceinline__ void attn_unit(const AtArgs& A, unsigned char* lds, int unit, int tid, int wave, int lane) {
;     ...
;         float m4[4], s4[4];
; #pragma unroll
;         for (int r = 0; r < 4; ++r) {
;             float m = sc[0][r];
; #pragma unroll
;             for (int kt = 1; kt < 9; ++kt) m = fmaxf(m, sc[kt][r]);
;             m = row16_max(m);
;             m4[r] = fmaxf(m, sink);
;             float s = 0.f;
; #pragma unroll
;             for (int kt = 0; kt < 9; ++kt) { const float e = __expf(sc[kt][r] - m4[r]); sc[kt][r] = e; s += e; }
;             s = row16_sum(s);
;             s4[r] = __builtin_amdgcn_rcpf(s + __expf(sink - m4[r]));
;         }
; #pragma unroll
;         for (int kt = 0; kt < 9; ++kt)
; #pragma unroll
;             for (int r = 0; r < 4; ++r) PS[(fq * 4 + r) * PST + kt * 16 + fr] = (bf16)f2bf(sc[kt][r] * s4[r]);
	v_rcp_f32_e32 v60, v60
	ds_write_b16 v79, v12 offset:96
	v_mov_b32_dpp v108, v95 quad_perm:[1,0,3,2] row_mask:0xf bank_mask:0xf
	v_max_f32_e32 v108, v108, v108
	v_max_f32_e32 v95, v95, v108
	v_mov_b32_e32 v108, 0
	v_mul_f32_e32 v14, v22, v60
	v_mul_f32_e32 v10, v97, v60
	v_mov_b32_dpp v108, v95 quad_perm:[2,3,0,1] row_mask:0xf bank_mask:0xf
	v_max_f32_e32 v108, v108, v108
	v_max_f32_e32 v95, v95, v108
	v_mov_b32_e32 v108, 0
	v_cvt_pk_bf16_f32 v14, v14, s0
	v_cvt_pk_bf16_f32 v10, v10, s0
	v_mov_b32_dpp v108, v95 row_half_mirror row_mask:0xf bank_mask:0xf
	v_max_f32_e32 v108, v108, v108
	v_max_f32_e32 v95, v95, v108
	v_mov_b32_e32 v108, 0
	ds_write_b16 v79, v14 offset:336
	ds_write_b16 v79, v10 offset:464
	v_mov_b32_dpp v108, v95 row_mirror row_mask:0xf bank_mask:0xf
	v_max3_f32 v95, v95, v108, v38
	v_sub_f32_e32 v18, v18, v95
	v_mul_f32_e32 v18, 0x3fb8aa3b, v18
	v_sub_f32_e32 v20, v20, v95
	v_exp_f32_e32 v18, v18
	v_mul_f32_e32 v20, 0x3fb8aa3b, v20
	v_sub_f32_e32 v23, v23, v95
	v_exp_f32_e32 v20, v20
	v_mul_f32_e32 v23, 0x3fb8aa3b, v23
	v_sub_f32_e32 v27, v27, v95
	v_exp_f32_e32 v23, v23
	v_mul_f32_e32 v27, 0x3fb8aa3b, v27
	v_sub_f32_e32 v57, v57, v95
	v_exp_f32_e32 v27, v27
	v_mul_f32_e32 v57, 0x3fb8aa3b, v57
	v_sub_f32_e32 v98, v98, v95
	v_add_f32_e32 v108, 0, v18
	v_exp_f32_e32 v57, v57
	v_mul_f32_e32 v98, 0x3fb8aa3b, v98
	v_sub_f32_e32 v102, v102, v95
	v_add_f32_e32 v108, v20, v108
	v_exp_f32_e32 v98, v98
	v_mul_f32_e32 v102, 0x3fb8aa3b, v102
	v_sub_f32_e32 v109, v123, v95
	v_add_f32_e32 v108, v23, v108
	v_exp_f32_e32 v102, v102
	v_mul_f32_e32 v109, 0x3fb8aa3b, v109
	v_sub_f32_e32 v59, v59, v95
	v_add_f32_e32 v108, v27, v108
	v_exp_f32_e32 v109, v109
	v_mul_f32_e32 v59, 0x3fb8aa3b, v59
	v_add_f32_e32 v108, v57, v108
	v_exp_f32_e32 v59, v59
	v_add_f32_e32 v108, v98, v108
	v_add_f32_e32 v108, v102, v108
	v_add_f32_e32 v108, v109, v108
	v_sub_f32_e32 v95, v38, v95
	v_add_f32_e32 v108, v59, v108
	v_mul_f32_e32 v95, 0x3fb8aa3b, v95
	v_exp_f32_e32 v95, v95
	v_add_f32_dpp v108, v108, v108 quad_perm:[1,0,3,2] row_mask:0xf bank_mask:0xf bound_ctrl:1
	v_mul_f32_e32 v12, v96, v60
	ds_write_b16 v79, v9 offset:224
	v_add_f32_dpp v108, v108, v108 quad_perm:[2,3,0,1] row_mask:0xf bank_mask:0xf bound_ctrl:1
	v_mul_f32_e32 v9, v103, v60
	ds_write_b16 v79, v8 offset:256
	v_add_f32_dpp v108, v108, v108 row_half_mirror row_mask:0xf bank_mask:0xf bound_ctrl:1
	v_mul_f32_e32 v8, v58, v60
	v_cvt_pk_bf16_f32 v12, v12, s0
	v_add_f32_dpp v108, v108, v108 row_mirror row_mask:0xf bank_mask:0xf bound_ctrl:1
	v_add_f32_e32 v95, v95, v108
	v_max3_f32 v108, v16, v17, v19
	v_max3_f32 v108, v108, v21, v25
	v_max3_f32 v108, v108, v28, v61
	v_max3_f32 v108, v108, v99, v31
	v_rcp_f32_e32 v95, v95
	v_cvt_pk_bf16_f32 v9, v9, s0
	v_mov_b32_dpp v110, v108 quad_perm:[1,0,3,2] row_mask:0xf bank_mask:0xf
	v_max_f32_e32 v110, v110, v110
	v_max_f32_e32 v108, v108, v110
	v_mov_b32_e32 v110, 0
	v_mul_f32_e32 v14, v18, v95
	v_mul_f32_e32 v10, v57, v95
	v_mov_b32_dpp v110, v108 quad_perm:[2,3,0,1] row_mask:0xf bank_mask:0xf
	v_max_f32_e32 v110, v110, v110
	v_max_f32_e32 v108, v108, v110
	v_mov_b32_e32 v110, 0
	v_cvt_pk_bf16_f32 v14, v14, s0
	v_cvt_pk_bf16_f32 v10, v10, s0
	v_mov_b32_dpp v110, v108 row_half_mirror row_mask:0xf bank_mask:0xf
	v_max_f32_e32 v110, v110, v110
	v_max_f32_e32 v108, v108, v110
	v_mov_b32_e32 v110, 0
	ds_write_b16 v79, v14 offset:672
	ds_write_b16 v79, v10 offset:800
	v_mov_b32_dpp v110, v108 row_mirror row_mask:0xf bank_mask:0xf
	v_max3_f32 v108, v108, v110, v38
	v_sub_f32_e32 v16, v16, v108
	v_mul_f32_e32 v16, 0x3fb8aa3b, v16
	v_sub_f32_e32 v17, v17, v108
	v_exp_f32_e32 v16, v16
	v_mul_f32_e32 v17, 0x3fb8aa3b, v17
	v_sub_f32_e32 v19, v19, v108
	v_exp_f32_e32 v17, v17
	v_mul_f32_e32 v19, 0x3fb8aa3b, v19
	v_sub_f32_e32 v21, v21, v108
	v_exp_f32_e32 v19, v19
	v_mul_f32_e32 v21, 0x3fb8aa3b, v21
	v_sub_f32_e32 v25, v25, v108
	v_exp_f32_e32 v21, v21
	v_mul_f32_e32 v25, 0x3fb8aa3b, v25
	v_sub_f32_e32 v28, v28, v108
	v_add_f32_e32 v110, 0, v16
	v_exp_f32_e32 v25, v25
	v_mul_f32_e32 v28, 0x3fb8aa3b, v28
	v_sub_f32_e32 v61, v61, v108
	v_add_f32_e32 v110, v17, v110
	v_exp_f32_e32 v28, v28
	v_mul_f32_e32 v61, 0x3fb8aa3b, v61
	v_sub_f32_e32 v99, v99, v108
	v_add_f32_e32 v110, v19, v110
	v_exp_f32_e32 v61, v61
	v_mul_f32_e32 v99, 0x3fb8aa3b, v99
	v_sub_f32_e32 v31, v31, v108
	v_add_f32_e32 v110, v21, v110
	v_exp_f32_e32 v99, v99
	v_mul_f32_e32 v31, 0x3fb8aa3b, v31
	v_add_f32_e32 v110, v25, v110
	v_exp_f32_e32 v31, v31
	v_add_f32_e32 v110, v28, v110
	v_add_f32_e32 v110, v61, v110
	v_add_f32_e32 v110, v99, v110
	v_sub_f32_e32 v108, v38, v108
	v_add_f32_e32 v110, v31, v110
	v_mul_f32_e32 v108, 0x3fb8aa3b, v108
	v_exp_f32_e32 v108, v108
	v_add_f32_dpp v110, v110, v110 quad_perm:[1,0,3,2] row_mask:0xf bank_mask:0xf bound_ctrl:1
	v_cvt_pk_bf16_f32 v8, v8, s0
	ds_write_b16 v79, v12 offset:432
	v_add_f32_dpp v110, v110, v110 quad_perm:[2,3,0,1] row_mask:0xf bank_mask:0xf bound_ctrl:1
	v_mul_f32_e32 v12, v27, v95
	ds_write_b16 v79, v9 offset:560
	v_add_f32_dpp v110, v110, v110 row_half_mirror row_mask:0xf bank_mask:0xf bound_ctrl:1
	v_mul_f32_e32 v9, v109, v95
	ds_write_b16 v79, v8 offset:592
	v_add_f32_dpp v110, v110, v110 row_mirror row_mask:0xf bank_mask:0xf bound_ctrl:1
	v_add_f32_e32 v108, v108, v110
	v_rcp_f32_e32 v108, v108
	v_mul_f32_e32 v8, v59, v95
	v_cvt_pk_bf16_f32 v12, v12, s0
	v_cvt_pk_bf16_f32 v9, v9, s0
	v_mul_f32_e32 v14, v16, v108
	v_mul_f32_e32 v10, v25, v108
	v_cvt_pk_bf16_f32 v14, v14, s0
	v_cvt_pk_bf16_f32 v10, v10, s0
	ds_write_b16 v79, v14 offset:1008
	v_mul_f32_e32 v14, v29, v30
	ds_write_b16 v79, v10 offset:1136
	v_mul_f32_e32 v10, v13, v30
; __device__ __forceinline__ unsigned f2bf(float f) { return pk2(f, f) & 0xffffu; }
; #define LDS_WAIT() asm volatile("s_waitcnt lgkmcnt(0)" ::: "memory")
; __device__ __forceinline__ void attn_unit(const AtArgs& A, unsigned char* lds, int unit, int tid, int wave, int lane) {
;     ...
; #pragma unroll
;         for (int kt = 0; kt < 9; ++kt)
; #pragma unroll
;             for (int r = 0; r < 4; ++r) PS[(fq * 4 + r) * PST + kt * 16 + fr] = (bf16)f2bf(sc[kt][r] * s4[r]);
; #pragma unroll
;         for (int r = 0; r < 4; ++r) PS[(fq * 4 + r) * PST + 144 + fr] = 0;
;         LDS_WAIT();
;         f32x4 o[4];
; #pragma unroll
;         for (int dt = 0; dt < 4; ++dt) o[dt] = (f32x4){0.f, 0.f, 0.f, 0.f};
; #pragma unroll
;         for (int ks = 0; ks < 5; ++ks) {
;             const bf16x8 pa = *(const bf16x8*)(PS + fr * PST + ks * 32 + fq * 8);
; #pragma unroll
;             for (int dt = 0; dt < 4; ++dt) {
;                 const bf16x8 vb = *(const bf16x8*)(VT + (dt * 16 + fr) * VST + (((((q0 + ks * 32) >> 3) + fq) ^ ((dt * 2 + (fr >> 3)) & 7)) << 3));
;                 o[dt] = __builtin_amdgcn_mfma_f32_16x16x32_bf16(pa, vb, o[dt], 0, 0, 0);
;             }
;         }
	v_cvt_pk_bf16_f32 v14, v14, s0
	v_cvt_pk_bf16_f32 v10, v10, s0
	ds_write_b16 v79, v14 offset:32
	v_mul_f32_e32 v14, v26, v60
	ds_write_b16 v79, v10 offset:160
	v_mul_f32_e32 v10, v100, v60
	v_cvt_pk_bf16_f32 v14, v14, s0
	v_cvt_pk_bf16_f32 v10, v10, s0
	ds_write_b16 v79, v14 offset:368
	v_mul_f32_e32 v14, v20, v95
	ds_write_b16 v79, v10 offset:496
	v_mul_f32_e32 v10, v98, v95
	v_cvt_pk_bf16_f32 v14, v14, s0
	v_cvt_pk_bf16_f32 v10, v10, s0
	ds_write_b16 v79, v14 offset:704
	v_mul_f32_e32 v14, v17, v108
	ds_write_b16 v79, v10 offset:832
	v_mul_f32_e32 v10, v28, v108
	v_cvt_pk_bf16_f32 v14, v14, s0
	v_cvt_pk_bf16_f32 v10, v10, s0
	ds_write_b16 v79, v14 offset:1040
	v_mul_f32_e32 v14, v15, v30
	ds_write_b16 v79, v10 offset:1168
	v_mul_f32_e32 v10, v11, v30
	v_cvt_pk_bf16_f32 v14, v14, s0
	v_cvt_pk_bf16_f32 v10, v10, s0
	ds_write_b16 v79, v14 offset:64
	v_mul_f32_e32 v14, v56, v60
	ds_write_b16 v79, v10 offset:192
	v_mul_f32_e32 v10, v101, v60
	v_cvt_pk_bf16_f32 v14, v14, s0
	v_cvt_pk_bf16_f32 v10, v10, s0
	ds_write_b16 v79, v14 offset:400
	v_mul_f32_e32 v14, v23, v95
	ds_write_b16 v79, v10 offset:528
	v_mul_f32_e32 v10, v102, v95
	v_cvt_pk_bf16_f32 v14, v14, s0
	v_cvt_pk_bf16_f32 v10, v10, s0
	v_cvt_pk_bf16_f32 v8, v8, s0
	ds_write_b16 v79, v14 offset:736
	v_mul_f32_e32 v14, v19, v108
	ds_write_b16 v79, v12 offset:768
	v_mul_f32_e32 v12, v21, v108
	ds_write_b16 v79, v10 offset:864
	v_mul_f32_e32 v10, v61, v108
	ds_write_b16 v79, v9 offset:896
	v_mul_f32_e32 v9, v99, v108
	ds_write_b16 v79, v8 offset:928
	v_mul_f32_e32 v8, v31, v108
	v_cvt_pk_bf16_f32 v14, v14, s0
	v_cvt_pk_bf16_f32 v12, v12, s0
	v_cvt_pk_bf16_f32 v10, v10, s0
	v_cvt_pk_bf16_f32 v9, v9, s0
	v_cvt_pk_bf16_f32 v8, v8, s0
	ds_write_b16 v79, v14 offset:1072
	ds_write_b16 v79, v12 offset:1104
	ds_write_b16 v79, v10 offset:1200
	ds_write_b16 v79, v9 offset:1232
	ds_write_b16 v79, v8 offset:1264
	ds_write_b16 v79, v39 offset:288
	ds_write_b16 v79, v39 offset:624
	ds_write_b16 v79, v39 offset:960
	ds_write_b16 v79, v39 offset:1296
	s_waitcnt lgkmcnt(0)
	ds_read_b128 v[8:11], v77
	v_add_u32_e32 v25, -8, v94
	v_xor_b32_e32 v12, v25, v78
	v_xor_b32_e32 v16, v25, v82
	v_xor_b32_e32 v20, v25, v83
	v_xor_b32_e32 v25, v25, v84
	v_lshl_add_u32 v12, v12, 4, v80
	v_lshl_add_u32 v16, v16, 4, v80
	v_lshl_add_u32 v20, v20, 4, v80
	v_lshl_add_u32 v25, v25, 4, v81
	ds_read_b128 v[12:15], v12 offset:36864
	ds_read_b128 v[16:19], v16 offset:47872
	ds_read_b128 v[20:23], v20 offset:58880
	ds_read_b128 v[26:29], v25 offset:33024
	v_add_u32_e32 v25, -4, v94
	v_xor_b32_e32 v30, v25, v78
	v_lshl_add_u32 v30, v30, 4, v80
	ds_read_b128 v[56:59], v30 offset:36864
	s_waitcnt lgkmcnt(4)
	v_mfma_f32_16x16x32_bf16 v[12:15], v[8:11], v[12:15], 0
	v_xor_b32_e32 v30, v25, v82
	v_lshl_add_u32 v30, v30, 4, v80
	v_mov_b32_e32 v95, v24
	s_waitcnt lgkmcnt(3)
	v_mfma_f32_16x16x32_bf16 v[16:19], v[8:11], v[16:19], 0
	s_waitcnt lgkmcnt(2)
	v_mfma_f32_16x16x32_bf16 v[20:23], v[8:11], v[20:23], 0
	s_waitcnt lgkmcnt(1)
	v_mfma_f32_16x16x32_bf16 v[8:11], v[8:11], v[26:29], 0
	ds_read_b128 v[26:29], v77 offset:64
	s_waitcnt lgkmcnt(0)
	v_mfma_f32_16x16x32_bf16 v[12:15], v[26:29], v[56:59], v[12:15]
	ds_read_b128 v[56:59], v30 offset:47872
	v_xor_b32_e32 v30, v25, v83
	v_lshl_add_u32 v30, v30, 4, v80
	s_waitcnt lgkmcnt(0)
	v_mfma_f32_16x16x32_bf16 v[16:19], v[26:29], v[56:59], v[16:19]
	ds_read_b128 v[56:59], v30 offset:58880
	v_xor_b32_e32 v25, v25, v84
	v_lshl_add_u32 v25, v25, 4, v81
	s_waitcnt lgkmcnt(0)
	v_mfma_f32_16x16x32_bf16 v[20:23], v[26:29], v[56:59], v[20:23]
	ds_read_b128 v[56:59], v25 offset:33024
	v_xor_b32_e32 v25, v94, v78
	v_lshl_add_u32 v25, v25, 4, v80
	s_waitcnt lgkmcnt(0)
	v_mfma_f32_16x16x32_bf16 v[8:11], v[26:29], v[56:59], v[8:11]
	ds_read_b128 v[26:29], v77 offset:128
	ds_read_b128 v[56:59], v25 offset:36864
	v_xor_b32_e32 v25, v94, v82
	v_lshl_add_u32 v25, v25, 4, v80
	s_waitcnt lgkmcnt(0)
	v_mfma_f32_16x16x32_bf16 v[12:15], v[26:29], v[56:59], v[12:15]
	ds_read_b128 v[56:59], v25 offset:47872
	v_xor_b32_e32 v25, v94, v83
	v_lshl_add_u32 v25, v25, 4, v80
	s_waitcnt lgkmcnt(0)
; __device__ __forceinline__ unsigned f2bf(float f) { return pk2(f, f) & 0xffffu; }
; #define LDS_WAIT() asm volatile("s_waitcnt lgkmcnt(0)" ::: "memory")
; __device__ __forceinline__ void attn_unit(const AtArgs& A, unsigned char* lds, int unit, int tid, int wave, int lane) {
;     ...
;         for (int ks = 0; ks < 5; ++ks) {
;             const bf16x8 pa = *(const bf16x8*)(PS + fr * PST + ks * 32 + fq * 8);
; #pragma unroll
;             for (int dt = 0; dt < 4; ++dt) {
;                 const bf16x8 vb = *(const bf16x8*)(VT + (dt * 16 + fr) * VST + (((((q0 + ks * 32) >> 3) + fq) ^ ((dt * 2 + (fr >> 3)) & 7)) << 3));
;                 o[dt] = __builtin_amdgcn_mfma_f32_16x16x32_bf16(pa, vb, o[dt], 0, 0, 0);
;             }
;         }
;         LDS_WAIT();
; #pragma unroll
;         for (int r = 0; r < 4; ++r)
; #pragma unroll
;             for (int dt = 0; dt < 4; ++dt) PS[(fq * 4 + r) * PST + dt * 16 + fr] = (bf16)f2bf(o[dt][r]);
;         LDS_WAIT();
; #pragma unroll
;         for (int j = 0; j < 2; ++j) {
;             const int tk = (lane >> 3) + 8 * j, c16 = lane & 7;
;             const size_t t = (size_t)b * SEQ + nb * 128 + q0 + tk;
;             *(u32x4*)(YB + t * 512 + hq * 64 + c16 * 8) = *(const u32x4*)(PS + tk * PST + c16 * 8);
;         }
;         LDS_WAIT();
	v_mfma_f32_16x16x32_bf16 v[16:19], v[26:29], v[56:59], v[16:19]
	ds_read_b128 v[56:59], v25 offset:58880
	v_add_u32_e32 v25, 4, v94
	s_waitcnt lgkmcnt(0)
	v_mfma_f32_16x16x32_bf16 v[56:59], v[26:29], v[56:59], v[20:23]
	s_nop 2
	v_xor_b32_e32 v20, v94, v84
	v_lshl_add_u32 v20, v20, 4, v81
	ds_read_b128 v[20:23], v20 offset:33024
	s_waitcnt lgkmcnt(0)
	v_mfma_f32_16x16x32_bf16 v[8:11], v[26:29], v[20:23], v[8:11]
	ds_read_b128 v[26:29], v77 offset:192
	v_xor_b32_e32 v20, v25, v78
	v_lshl_add_u32 v20, v20, 4, v80
	ds_read_b128 v[20:23], v20 offset:36864
	s_waitcnt lgkmcnt(0)
	v_mfma_f32_16x16x32_bf16 v[20:23], v[26:29], v[20:23], v[12:15]
	s_nop 2
	v_xor_b32_e32 v12, v25, v82
	v_lshl_add_u32 v12, v12, 4, v80
	ds_read_b128 v[12:15], v12 offset:47872
	s_waitcnt lgkmcnt(0)
	v_mfma_f32_16x16x32_bf16 v[16:19], v[26:29], v[12:15], v[16:19]
	v_xor_b32_e32 v12, v25, v83
	v_lshl_add_u32 v12, v12, 4, v80
	ds_read_b128 v[12:15], v12 offset:58880
	v_xor_b32_e32 v25, v25, v84
	v_lshl_add_u32 v25, v25, 4, v81
	s_waitcnt lgkmcnt(0)
	v_mfma_f32_16x16x32_bf16 v[12:15], v[26:29], v[12:15], v[56:59]
	s_nop 2
	ds_read_b128 v[56:59], v25 offset:33024
	v_add_u32_e32 v25, 8, v94
	s_waitcnt lgkmcnt(0)
	v_mfma_f32_16x16x32_bf16 v[8:11], v[26:29], v[56:59], v[8:11]
	ds_read_b128 v[26:29], v77 offset:256
	v_xor_b32_e32 v30, v25, v78
	v_lshl_add_u32 v30, v30, 4, v80
	ds_read_b128 v[56:59], v30 offset:36864
	v_xor_b32_e32 v30, v25, v82
	v_lshl_add_u32 v30, v30, 4, v80
	s_waitcnt lgkmcnt(0)
	v_mfma_f32_16x16x32_bf16 v[20:23], v[26:29], v[56:59], v[20:23]
	ds_read_b128 v[56:59], v30 offset:47872
	v_xor_b32_e32 v30, v25, v83
	v_lshl_add_u32 v30, v30, 4, v80
	s_waitcnt lgkmcnt(0)
	v_mfma_f32_16x16x32_bf16 v[16:19], v[26:29], v[56:59], v[16:19]
	ds_read_b128 v[56:59], v30 offset:58880
	v_xor_b32_e32 v25, v25, v84
	v_lshl_add_u32 v25, v25, 4, v81
	s_waitcnt lgkmcnt(0)
	v_mfma_f32_16x16x32_bf16 v[12:15], v[26:29], v[56:59], v[12:15]
	ds_read_b128 v[56:59], v25 offset:33024
	s_waitcnt lgkmcnt(0)
	v_cvt_pk_bf16_f32 v20, v20, s0
	s_waitcnt lgkmcnt(0)
	v_mfma_f32_16x16x32_bf16 v[8:11], v[26:29], v[56:59], v[8:11]
	v_cvt_pk_bf16_f32 v16, v16, s0
	s_nop 2
	v_cvt_pk_bf16_f32 v12, v12, s0
	ds_write_b16 v79, v20
	s_nop 1
	v_cvt_pk_bf16_f32 v8, v8, s0
	ds_write_b16 v79, v8 offset:96
	v_cvt_pk_bf16_f32 v8, v21, s0
	ds_write_b16 v79, v8 offset:336
	v_cvt_pk_bf16_f32 v8, v17, s0
	ds_write_b16 v79, v8 offset:368
	v_cvt_pk_bf16_f32 v8, v13, s0
	ds_write_b16 v79, v8 offset:400
	v_cvt_pk_bf16_f32 v8, v9, s0
	ds_write_b16 v79, v8 offset:432
	v_cvt_pk_bf16_f32 v8, v22, s0
	ds_write_b16 v79, v8 offset:672
	v_cvt_pk_bf16_f32 v8, v18, s0
	ds_write_b16 v79, v8 offset:704
	v_cvt_pk_bf16_f32 v8, v14, s0
	ds_write_b16 v79, v8 offset:736
	v_cvt_pk_bf16_f32 v8, v10, s0
	ds_write_b16 v79, v8 offset:768
	v_cvt_pk_bf16_f32 v8, v23, s0
	ds_write_b16 v79, v8 offset:1008
	v_cvt_pk_bf16_f32 v8, v19, s0
	ds_write_b16 v79, v8 offset:1040
	v_cvt_pk_bf16_f32 v8, v15, s0
	ds_write_b16 v79, v8 offset:1072
	v_cvt_pk_bf16_f32 v8, v11, s0
	ds_write_b16 v79, v16 offset:32
	ds_write_b16 v79, v12 offset:64
	ds_write_b16 v79, v8 offset:1104
	s_waitcnt lgkmcnt(0)
	ds_read_b128 v[8:11], v92
	v_lshl_add_u64 v[12:13], v[52:53], 0, s[20:21]
	s_mov_b32 s0, 0x1d800000
	v_add_co_u32_e32 v14, vcc, s0, v12
	s_mov_b32 s0, 0x1d802000
	s_nop 0
	v_addc_co_u32_e32 v15, vcc, 0, v13, vcc
	s_waitcnt lgkmcnt(0)
	global_store_dwordx4 v[14:15], v[8:11], off
	ds_read_b128 v[8:11], v92 offset:2688
	v_add_co_u32_e32 v12, vcc, s0, v12
	s_add_u32 s20, s20, 0x4000
	s_nop 0
	v_addc_co_u32_e32 v13, vcc, 0, v13, vcc
	s_waitcnt lgkmcnt(0)
	global_store_dwordx4 v[12:13], v[8:11], off
	s_waitcnt lgkmcnt(0)
	s_addc_u32 s21, s21, 0
	s_mov_b64 s[0:1], 0x400
	s_waitcnt vmcnt(2)
	v_mov_b64_e32 v[14:15], v[6:7]
	v_mov_b64_e32 v[10:11], v[2:3]
	v_add_u32_e32 v94, 2, v94
	v_lshl_add_u64 v[54:55], v[54:55], 0, s[0:1]
	s_cmp_lg_u32 s2, 64
	v_mov_b64_e32 v[12:13], v[4:5]
	v_mov_b64_e32 v[8:9], v[0:1]
	s_cbranch_scc0 .LBB0_492
